# mixa: first PV group's 8 transposed V reads issued ~90 VALU instructions earlier (inside the last exp block) into v[164:179]
# baseline (speedup 1.0000x reference)
; #define SBAR() __builtin_amdgcn_sched_barrier(0)
; __device__ __forceinline__ void mixa_run(int b, int h, int br, int res, int n0, const bf16_t* __restrict__ proj, const float* __restrict__ btab,
;                                          bf16_t* __restrict__ OA, float* __restrict__ LSE, char* lds) {
;     ...
;     constexpr float C = SCALE * 1.4426950408889634f;
;     float mx = -3.0e38f;
; #pragma unroll
;     for (int kb = 0; kb < 5; ++kb) { const int tile = (q32 + kb) >> 1;
;       const float* tb = ((tile == 0 && T0 < 0) || (tile == 3 && T0 + 3 >= nbt)) ? btn : btl;
; #pragma unroll
;       for (int r = 0; r < 16; ++r) { const int cidx = 32 * kb + (r & 3) + 8 * (r >> 2);
;         const float v = fmaf(p[kb][r], C, tb[cidx]);
;         p[kb][r] = v; mx = fmaxf(mx, v); }
;       SBAR(); }
;     { auto rr = __builtin_amdgcn_permlane32_swap(__float_as_uint(mx), __float_as_uint(mx), false, false); mx = fmaxf(__uint_as_float(rr[0]), __uint_as_float(rr[1])); }
.LBB0_319:
	s_add_i32 s12, s72, s22
	s_cmp_eq_u32 s12, 0
	s_cselect_b64 s[12:13], -1, 0
	s_add_i32 s16, s84, s86
	s_add_i32 s16, s16, 2
	s_cmp_lt_i32 s16, s71
	s_cselect_b64 vcc, -1, 0
	s_and_b64 s[16:17], s[54:55], s[12:13]
	s_add_i32 s27, 0, 0x20800
	s_and_b64 s[16:17], s[16:17], exec
	s_cselect_b32 s16, s27, s38
	v_lshlrev_b32_e32 v231, 2, v200
	v_add_u32_e32 v162, s16, v231
	ds_read2_b32 v[160:161], v162 offset0:32 offset1:33
	s_mov_b32 s16, 0xff61b1e6
	s_waitcnt lgkmcnt(0)
	v_fmamk_f32 v115, v66, 0x3e0293ee, v160
	v_fmac_f32_e32 v161, 0x3e0293ee, v67
	ds_read2_b32 v[66:67], v162 offset0:34 offset1:35
	v_max3_f32 v160, v115, s16, v161
	s_waitcnt lgkmcnt(0)
	v_fmamk_f32 v66, v68, 0x3e0293ee, v66
	v_fmac_f32_e32 v67, 0x3e0293ee, v69
	ds_read2_b32 v[68:69], v162 offset0:40 offset1:41
	v_max3_f32 v160, v160, v66, v67
	s_waitcnt lgkmcnt(0)
	v_fmamk_f32 v68, v70, 0x3e0293ee, v68
	v_fmac_f32_e32 v69, 0x3e0293ee, v71
	ds_read2_b32 v[70:71], v162 offset0:42 offset1:43
	v_max3_f32 v160, v160, v68, v69
	s_waitcnt lgkmcnt(0)
	v_fmamk_f32 v70, v72, 0x3e0293ee, v70
	v_fmac_f32_e32 v71, 0x3e0293ee, v73
	ds_read2_b32 v[72:73], v162 offset0:48 offset1:49
	v_max3_f32 v160, v160, v70, v71
	s_waitcnt lgkmcnt(0)
	v_fmamk_f32 v72, v74, 0x3e0293ee, v72
	v_fmac_f32_e32 v73, 0x3e0293ee, v75
	ds_read2_b32 v[74:75], v162 offset0:50 offset1:51
	v_max3_f32 v163, v160, v72, v73
	s_waitcnt lgkmcnt(0)
	v_fmamk_f32 v160, v76, 0x3e0293ee, v74
	v_fmac_f32_e32 v75, 0x3e0293ee, v77
	ds_read2_b32 v[76:77], v162 offset0:56 offset1:57
	v_max3_f32 v74, v163, v160, v75
	s_waitcnt lgkmcnt(0)
	v_fmamk_f32 v76, v78, 0x3e0293ee, v76
	v_fmac_f32_e32 v77, 0x3e0293ee, v79
	ds_read2_b32 v[78:79], v162 offset0:58 offset1:59
	v_max3_f32 v74, v74, v76, v77
	s_waitcnt lgkmcnt(0)
	v_fmamk_f32 v230, v80, 0x3e0293ee, v78
	v_fmac_f32_e32 v79, 0x3e0293ee, v81
	v_max3_f32 v74, v74, v230, v79
	s_and_b64 s[12:13], s[56:57], s[12:13]
	s_and_b64 s[12:13], s[12:13], exec
	s_cselect_b32 s12, s27, s38
	v_add_u32_e32 v162, s12, v231
	ds_read2_b32 v[80:81], v162 offset0:64 offset1:65
	s_waitcnt lgkmcnt(0)
	v_fmamk_f32 v78, v50, 0x3e0293ee, v80
	v_fmac_f32_e32 v81, 0x3e0293ee, v51
	ds_read2_b32 v[50:51], v162 offset0:66 offset1:67
	v_max3_f32 v74, v74, v78, v81
	s_waitcnt lgkmcnt(0)
	v_fmamk_f32 v50, v52, 0x3e0293ee, v50
	v_fmac_f32_e32 v51, 0x3e0293ee, v53
	ds_read2_b32 v[52:53], v162 offset0:72 offset1:73
	v_max3_f32 v74, v74, v50, v51
	s_waitcnt lgkmcnt(0)
	v_fmamk_f32 v52, v54, 0x3e0293ee, v52
	v_fmac_f32_e32 v53, 0x3e0293ee, v55
	ds_read2_b32 v[54:55], v162 offset0:74 offset1:75
	v_max3_f32 v74, v74, v52, v53
	s_waitcnt lgkmcnt(0)
	v_fmamk_f32 v54, v56, 0x3e0293ee, v54
	v_fmac_f32_e32 v55, 0x3e0293ee, v57
	ds_read2_b32 v[56:57], v162 offset0:80 offset1:81
	v_max3_f32 v74, v74, v54, v55
	s_waitcnt lgkmcnt(0)
	v_fmamk_f32 v56, v58, 0x3e0293ee, v56
	v_fmac_f32_e32 v57, 0x3e0293ee, v59
	ds_read2_b32 v[58:59], v162 offset0:82 offset1:83
	v_max3_f32 v74, v74, v56, v57
	s_waitcnt lgkmcnt(0)
	v_fmamk_f32 v58, v60, 0x3e0293ee, v58
	v_fmac_f32_e32 v59, 0x3e0293ee, v61
	ds_read2_b32 v[60:61], v162 offset0:88 offset1:89
	ds_read2_b32 v[162:163], v162 offset0:90 offset1:91
	v_max3_f32 v74, v74, v58, v59
	s_waitcnt lgkmcnt(1)
	v_fmamk_f32 v60, v62, 0x3e0293ee, v60
	v_fmac_f32_e32 v61, 0x3e0293ee, v63
	v_max3_f32 v62, v74, v60, v61
	s_waitcnt lgkmcnt(0)
	v_fmamk_f32 v162, v64, 0x3e0293ee, v162
	v_fmac_f32_e32 v163, 0x3e0293ee, v65
	v_max3_f32 v64, v62, v162, v163
	ds_read2_b32 v[62:63], v228 offset0:96 offset1:97
	ds_read2_b32 v[164:165], v228 offset0:104 offset1:105
	ds_read2_b32 v[168:169], v228 offset0:112 offset1:113
	ds_read2_b32 v[172:173], v228 offset0:120 offset1:121
	ds_read2_b32 v[166:167], v228 offset0:106 offset1:107
	ds_read2_b32 v[170:171], v228 offset0:114 offset1:115
	s_waitcnt lgkmcnt(5)
	v_fmamk_f32 v62, v34, 0x3e0293ee, v62
	v_fmac_f32_e32 v63, 0x3e0293ee, v35
	v_max3_f32 v34, v64, v62, v63
	ds_read2_b32 v[64:65], v228 offset0:98 offset1:99
	s_waitcnt lgkmcnt(5)
	v_fmamk_f32 v80, v38, 0x3e0293ee, v164
	v_fmac_f32_e32 v165, 0x3e0293ee, v39
	s_waitcnt lgkmcnt(2)
	v_fmamk_f32 v164, v40, 0x3e0293ee, v166
	v_fmamk_f32 v166, v42, 0x3e0293ee, v168
	s_waitcnt lgkmcnt(0)
	v_fmamk_f32 v64, v36, 0x3e0293ee, v64
	v_fmac_f32_e32 v65, 0x3e0293ee, v37
	v_max3_f32 v34, v34, v64, v65
	v_fmamk_f32 v168, v44, 0x3e0293ee, v170
	v_fmamk_f32 v170, v46, 0x3e0293ee, v172
	v_fmac_f32_e32 v173, 0x3e0293ee, v47
	ds_read2_b32 v[46:47], v228 offset0:122 offset1:123
	v_max3_f32 v34, v34, v80, v165
	v_fmac_f32_e32 v167, 0x3e0293ee, v41
	v_max3_f32 v34, v34, v164, v167
	v_fmac_f32_e32 v169, 0x3e0293ee, v43
	v_max3_f32 v34, v34, v166, v169
	v_fmac_f32_e32 v171, 0x3e0293ee, v45
	v_max3_f32 v34, v34, v168, v171
	v_max3_f32 v34, v34, v170, v173
	s_waitcnt lgkmcnt(0)
	v_fmamk_f32 v46, v48, 0x3e0293ee, v46
	v_fmac_f32_e32 v47, 0x3e0293ee, v49
	v_max3_f32 v34, v34, v46, v47
	s_or_b64 s[12:13], s[58:59], vcc
	s_and_b64 s[12:13], s[12:13], exec
	s_cselect_b32 s12, s38, s27
	v_add_u32_e32 v35, s12, v231
	ds_read2_b32 v[174:175], v35 offset0:128 offset1:129
	ds_read2_b32 v[176:177], v35 offset0:130 offset1:131
	ds_read2_b32 v[178:179], v35 offset0:136 offset1:137
	s_waitcnt lgkmcnt(2)
	v_fmamk_f32 v172, v18, 0x3e0293ee, v174
	s_waitcnt lgkmcnt(1)
	v_fmamk_f32 v174, v20, 0x3e0293ee, v176
	s_waitcnt lgkmcnt(0)
	v_fmamk_f32 v176, v22, 0x3e0293ee, v178
	v_fmac_f32_e32 v179, 0x3e0293ee, v23
	ds_read2_b32 v[22:23], v35 offset0:138 offset1:139
	v_fmac_f32_e32 v175, 0x3e0293ee, v19
	v_max3_f32 v18, v34, v172, v175
	v_fmac_f32_e32 v177, 0x3e0293ee, v21
	v_max3_f32 v18, v18, v174, v177
	s_waitcnt lgkmcnt(0)
; #define SBAR() __builtin_amdgcn_sched_barrier(0)
; __device__ __forceinline__ void mixa_run(int b, int h, int br, int res, int n0, const bf16_t* __restrict__ proj, const float* __restrict__ btab,
;                                          bf16_t* __restrict__ OA, float* __restrict__ LSE, char* lds) {
;     ...
;         p[kb][r] = v; mx = fmaxf(mx, v); }
;       SBAR(); }
;     { auto rr = __builtin_amdgcn_permlane32_swap(__float_as_uint(mx), __float_as_uint(mx), false, false); mx = fmaxf(__uint_as_float(rr[0]), __uint_as_float(rr[1])); }
;     float sum = 0.f;
;     bf16x8 pa[10];
; #pragma unroll
;     for (int kb = 0; kb < 5; ++kb) {
; #pragma unroll
;       for (int r = 0; r < 16; ++r) { const float e = __builtin_amdgcn_exp2f(p[kb][r] - mx); p[kb][r] = e; sum += e; }
;       ATT_PK4(p[kb], 0, pa[2 * kb]); ATT_PK4(p[kb], 8, pa[2 * kb + 1]); SBAR(); }
	v_fmamk_f32 v22, v24, 0x3e0293ee, v22
	v_fmac_f32_e32 v23, 0x3e0293ee, v25
	ds_read2_b32 v[24:25], v35 offset0:144 offset1:145
	v_max3_f32 v18, v18, v176, v179
	v_max3_f32 v18, v18, v22, v23
	s_waitcnt lgkmcnt(0)
	v_fmamk_f32 v24, v26, 0x3e0293ee, v24
	v_fmac_f32_e32 v25, 0x3e0293ee, v27
	ds_read2_b32 v[26:27], v35 offset0:146 offset1:147
	v_max3_f32 v18, v18, v24, v25
	s_waitcnt lgkmcnt(0)
	v_fmamk_f32 v26, v28, 0x3e0293ee, v26
	v_fmac_f32_e32 v27, 0x3e0293ee, v29
	ds_read2_b32 v[28:29], v35 offset0:152 offset1:153
	v_max3_f32 v18, v18, v26, v27
	s_waitcnt lgkmcnt(0)
	v_fmamk_f32 v28, v30, 0x3e0293ee, v28
	v_fmac_f32_e32 v29, 0x3e0293ee, v31
	ds_read2_b32 v[30:31], v35 offset0:154 offset1:155
	v_max3_f32 v18, v18, v28, v29
	s_waitcnt lgkmcnt(0)
	v_fmamk_f32 v178, v32, 0x3e0293ee, v30
	v_fmac_f32_e32 v31, 0x3e0293ee, v33
	v_max3_f32 v18, v18, v178, v31
	s_or_b64 s[12:13], s[60:61], vcc
	s_and_b64 s[12:13], s[12:13], exec
	s_cselect_b32 s12, s38, s27
	v_add_u32_e32 v19, s12, v231
	ds_read2_b32 v[32:33], v19 offset0:160 offset1:161
	s_waitcnt lgkmcnt(0)
	v_fmamk_f32 v30, v2, 0x3e0293ee, v32
	v_fmac_f32_e32 v33, 0x3e0293ee, v3
	ds_read2_b32 v[2:3], v19 offset0:162 offset1:163
	v_max3_f32 v18, v18, v30, v33
	s_waitcnt lgkmcnt(0)
	v_fmamk_f32 v2, v4, 0x3e0293ee, v2
	v_fmac_f32_e32 v3, 0x3e0293ee, v5
	ds_read2_b32 v[4:5], v19 offset0:168 offset1:169
	v_max3_f32 v18, v18, v2, v3
	s_waitcnt lgkmcnt(0)
	v_fmamk_f32 v4, v6, 0x3e0293ee, v4
	v_fmac_f32_e32 v5, 0x3e0293ee, v7
	ds_read2_b32 v[6:7], v19 offset0:170 offset1:171
	v_max3_f32 v18, v18, v4, v5
	s_waitcnt lgkmcnt(0)
	v_fmamk_f32 v6, v8, 0x3e0293ee, v6
	v_fmac_f32_e32 v7, 0x3e0293ee, v9
	ds_read2_b32 v[8:9], v19 offset0:176 offset1:177
	v_max3_f32 v18, v18, v6, v7
	s_waitcnt lgkmcnt(0)
	v_fmamk_f32 v8, v10, 0x3e0293ee, v8
	v_fmac_f32_e32 v9, 0x3e0293ee, v11
	ds_read2_b32 v[10:11], v19 offset0:178 offset1:179
	v_max3_f32 v18, v18, v8, v9
	s_waitcnt lgkmcnt(0)
	v_fmamk_f32 v10, v12, 0x3e0293ee, v10
	v_fmac_f32_e32 v11, 0x3e0293ee, v13
	ds_read2_b32 v[12:13], v19 offset0:184 offset1:185
	v_max3_f32 v18, v18, v10, v11
	s_waitcnt lgkmcnt(0)
	v_fmamk_f32 v12, v14, 0x3e0293ee, v12
	v_fmac_f32_e32 v13, 0x3e0293ee, v15
	ds_read2_b32 v[14:15], v19 offset0:186 offset1:187
	v_max3_f32 v18, v18, v12, v13
	s_waitcnt lgkmcnt(0)
	v_fmamk_f32 v14, v16, 0x3e0293ee, v14
	v_fmac_f32_e32 v15, 0x3e0293ee, v17
	v_max3_f32 v16, v18, v14, v15
	v_mov_b32_e32 v17, v16
	s_nop 1
	v_permlane32_swap_b32_e32 v16, v17
	v_max_f32_e32 v17, v17, v17
	v_max_f32_e32 v16, v16, v16
	v_max_f32_e32 v74, v16, v17
	v_sub_f32_e32 v16, v115, v74
	v_exp_f32_e32 v16, v16
	v_sub_f32_e32 v17, v161, v74
	v_exp_f32_e32 v17, v17
	v_sub_f32_e32 v18, v66, v74
	v_exp_f32_e32 v19, v18
	v_sub_f32_e32 v18, v67, v74
	v_exp_f32_e32 v20, v18
	v_sub_f32_e32 v21, v68, v74
	v_add_f32_e32 v18, 0, v16
	v_exp_f32_e32 v21, v21
	v_sub_f32_e32 v32, v69, v74
	v_add_f32_e32 v18, v17, v18
	v_exp_f32_e32 v32, v32
	v_sub_f32_e32 v34, v70, v74
	v_add_f32_e32 v18, v19, v18
	v_exp_f32_e32 v34, v34
	v_sub_f32_e32 v35, v71, v74
	v_add_f32_e32 v18, v20, v18
	v_exp_f32_e32 v35, v35
	v_sub_f32_e32 v36, v72, v74
	v_add_f32_e32 v18, v21, v18
	v_exp_f32_e32 v36, v36
	v_sub_f32_e32 v37, v73, v74
	v_add_f32_e32 v18, v32, v18
	v_exp_f32_e32 v37, v37
	v_sub_f32_e32 v38, v160, v74
	v_add_f32_e32 v18, v34, v18
	v_exp_f32_e32 v38, v38
	v_sub_f32_e32 v39, v75, v74
	v_add_f32_e32 v18, v35, v18
	v_exp_f32_e32 v39, v39
	v_sub_f32_e32 v40, v76, v74
	v_add_f32_e32 v18, v36, v18
	v_exp_f32_e32 v40, v40
	v_sub_f32_e32 v41, v77, v74
	v_add_f32_e32 v18, v37, v18
	v_exp_f32_e32 v41, v41
	v_sub_f32_e32 v42, v230, v74
	v_add_f32_e32 v18, v38, v18
	v_exp_f32_e32 v42, v42
	v_sub_f32_e32 v43, v79, v74
	v_add_f32_e32 v18, v39, v18
	v_exp_f32_e32 v43, v43
	v_add_f32_e32 v18, v40, v18
	v_add_f32_e32 v18, v41, v18
	v_add_f32_e32 v18, v42, v18
	v_add_f32_e32 v44, v43, v18
	v_cvt_pk_bf16_f32 v18, v16, v17
	v_cvt_pk_bf16_f32 v19, v19, v20
	v_cvt_pk_bf16_f32 v20, v21, v32
	v_cvt_pk_bf16_f32 v21, v34, v35
	s_nop 0
	v_permlane32_swap_b32_e32 v18, v20
	v_permlane32_swap_b32_e32 v19, v21
	v_cvt_pk_bf16_f32 v34, v36, v37
	v_cvt_pk_bf16_f32 v35, v38, v39
	v_cvt_pk_bf16_f32 v36, v40, v41
	v_cvt_pk_bf16_f32 v37, v42, v43
	s_nop 0
	v_permlane32_swap_b32_e32 v34, v36
	v_permlane32_swap_b32_e32 v35, v37
	v_sub_f32_e32 v16, v78, v74
	v_exp_f32_e32 v16, v16
	v_sub_f32_e32 v17, v81, v74
	v_exp_f32_e32 v17, v17
	v_sub_f32_e32 v32, v50, v74
	v_exp_f32_e32 v32, v32
	v_sub_f32_e32 v38, v51, v74
	v_exp_f32_e32 v39, v38
	v_sub_f32_e32 v40, v52, v74
	v_add_f32_e32 v38, v16, v44
	v_exp_f32_e32 v40, v40
	v_sub_f32_e32 v41, v53, v74
	v_add_f32_e32 v38, v17, v38
	v_exp_f32_e32 v41, v41
	v_sub_f32_e32 v42, v54, v74
	v_add_f32_e32 v38, v32, v38
	v_exp_f32_e32 v42, v42
	v_sub_f32_e32 v43, v55, v74
	v_add_f32_e32 v38, v39, v38
	v_exp_f32_e32 v43, v43
	v_sub_f32_e32 v44, v56, v74
	v_add_f32_e32 v38, v40, v38
	v_exp_f32_e32 v44, v44
	v_sub_f32_e32 v45, v57, v74
	v_add_f32_e32 v38, v41, v38
	v_exp_f32_e32 v45, v45
	v_sub_f32_e32 v48, v58, v74
	v_add_f32_e32 v38, v42, v38
	v_exp_f32_e32 v48, v48
	v_sub_f32_e32 v49, v59, v74
	v_add_f32_e32 v38, v43, v38
	v_exp_f32_e32 v49, v49
	v_sub_f32_e32 v50, v60, v74
	v_add_f32_e32 v38, v44, v38
	v_exp_f32_e32 v50, v50
	v_sub_f32_e32 v51, v61, v74
	v_add_f32_e32 v38, v45, v38
	v_exp_f32_e32 v51, v51
	v_sub_f32_e32 v52, v162, v74
	v_add_f32_e32 v38, v48, v38
	v_exp_f32_e32 v52, v52
	v_sub_f32_e32 v53, v163, v74
	v_add_f32_e32 v38, v49, v38
	v_exp_f32_e32 v53, v53
	v_add_f32_e32 v38, v50, v38
	v_add_f32_e32 v38, v51, v38
	v_add_f32_e32 v38, v52, v38
	v_add_f32_e32 v54, v53, v38
	v_cvt_pk_bf16_f32 v38, v16, v17
; #define SBAR() __builtin_amdgcn_sched_barrier(0)
; __device__ __forceinline__ void mixa_run(int b, int h, int br, int res, int n0, const bf16_t* __restrict__ proj, const float* __restrict__ btab,
;                                          bf16_t* __restrict__ OA, float* __restrict__ LSE, char* lds) {
;     ...
;     for (int kb = 0; kb < 5; ++kb) {
; #pragma unroll
;       for (int r = 0; r < 16; ++r) { const float e = __builtin_amdgcn_exp2f(p[kb][r] - mx); p[kb][r] = e; sum += e; }
;       ATT_PK4(p[kb], 0, pa[2 * kb]); ATT_PK4(p[kb], 8, pa[2 * kb + 1]); SBAR(); }
;     { auto rr = __builtin_amdgcn_permlane32_swap(__float_as_uint(sum), __float_as_uint(sum), false, false); sum = __uint_as_float(rr[0]) + __uint_as_float(rr[1]); }
;     f32x16 o0 = f32x16{}, o1 = f32x16{};
	v_cvt_pk_bf16_f32 v39, v32, v39
	v_cvt_pk_bf16_f32 v40, v40, v41
	v_cvt_pk_bf16_f32 v41, v42, v43
	v_cvt_pk_bf16_f32 v42, v44, v45
	v_cvt_pk_bf16_f32 v43, v48, v49
	v_cvt_pk_bf16_f32 v44, v50, v51
	v_cvt_pk_bf16_f32 v45, v52, v53
	v_permlane32_swap_b32_e32 v38, v40
	v_permlane32_swap_b32_e32 v39, v41
	v_permlane32_swap_b32_e32 v42, v44
	v_permlane32_swap_b32_e32 v43, v45
	v_sub_f32_e32 v16, v62, v74
	v_exp_f32_e32 v16, v16
	v_sub_f32_e32 v17, v63, v74
	v_exp_f32_e32 v17, v17
	v_sub_f32_e32 v32, v64, v74
	v_exp_f32_e32 v32, v32
	v_sub_f32_e32 v48, v65, v74
	v_exp_f32_e32 v48, v48
	v_sub_f32_e32 v50, v80, v74
	v_add_f32_e32 v49, v16, v54
	v_exp_f32_e32 v50, v50
	v_sub_f32_e32 v51, v165, v74
	v_add_f32_e32 v49, v17, v49
	v_exp_f32_e32 v51, v51
	v_sub_f32_e32 v52, v164, v74
	v_add_f32_e32 v49, v32, v49
	v_exp_f32_e32 v52, v52
	v_sub_f32_e32 v53, v167, v74
	v_add_f32_e32 v49, v48, v49
	v_exp_f32_e32 v53, v53
	v_sub_f32_e32 v54, v166, v74
	v_add_f32_e32 v49, v50, v49
	v_exp_f32_e32 v54, v54
	v_sub_f32_e32 v55, v169, v74
	v_add_f32_e32 v49, v51, v49
	v_exp_f32_e32 v55, v55
	v_sub_f32_e32 v56, v168, v74
	v_add_f32_e32 v49, v52, v49
	v_exp_f32_e32 v56, v56
	v_sub_f32_e32 v57, v171, v74
	v_add_f32_e32 v49, v53, v49
	v_exp_f32_e32 v57, v57
	v_sub_f32_e32 v58, v170, v74
	v_add_f32_e32 v49, v54, v49
	v_exp_f32_e32 v58, v58
	v_sub_f32_e32 v59, v173, v74
	v_add_f32_e32 v49, v55, v49
	v_exp_f32_e32 v59, v59
	v_sub_f32_e32 v46, v46, v74
	v_add_f32_e32 v49, v56, v49
	v_exp_f32_e32 v60, v46
	v_sub_f32_e32 v46, v47, v74
	v_add_f32_e32 v49, v57, v49
	v_exp_f32_e32 v61, v46
	v_add_f32_e32 v46, v58, v49
	v_add_f32_e32 v46, v59, v46
	v_add_f32_e32 v46, v60, v46
	v_add_f32_e32 v62, v61, v46
	v_cvt_pk_bf16_f32 v46, v16, v17
	v_cvt_pk_bf16_f32 v47, v32, v48
	v_cvt_pk_bf16_f32 v48, v50, v51
	v_cvt_pk_bf16_f32 v49, v52, v53
	v_cvt_pk_bf16_f32 v50, v54, v55
	v_cvt_pk_bf16_f32 v51, v56, v57
	v_cvt_pk_bf16_f32 v52, v58, v59
	v_cvt_pk_bf16_f32 v53, v60, v61
	v_permlane32_swap_b32_e32 v46, v48
	v_permlane32_swap_b32_e32 v47, v49
	v_permlane32_swap_b32_e32 v50, v52
	v_permlane32_swap_b32_e32 v51, v53
	v_sub_f32_e32 v16, v172, v74
	v_exp_f32_e32 v16, v16
	v_sub_f32_e32 v17, v175, v74
	v_exp_f32_e32 v17, v17
	v_sub_f32_e32 v32, v174, v74
	v_exp_f32_e32 v32, v32
	v_sub_f32_e32 v54, v177, v74
	v_exp_f32_e32 v55, v54
	v_sub_f32_e32 v56, v176, v74
	v_add_f32_e32 v54, v16, v62
	v_exp_f32_e32 v56, v56
	v_sub_f32_e32 v57, v179, v74
	v_add_f32_e32 v54, v17, v54
	v_exp_f32_e32 v57, v57
	v_sub_f32_e32 v22, v22, v74
	v_add_f32_e32 v54, v32, v54
	v_exp_f32_e32 v22, v22
	v_sub_f32_e32 v23, v23, v74
	v_add_f32_e32 v54, v55, v54
	v_exp_f32_e32 v23, v23
	v_sub_f32_e32 v24, v24, v74
	v_add_f32_e32 v54, v56, v54
	v_exp_f32_e32 v24, v24
	v_sub_f32_e32 v25, v25, v74
	v_add_f32_e32 v54, v57, v54
	v_exp_f32_e32 v25, v25
	v_sub_f32_e32 v26, v26, v74
	v_add_f32_e32 v54, v22, v54
	v_exp_f32_e32 v26, v26
	v_sub_f32_e32 v27, v27, v74
	v_add_f32_e32 v54, v23, v54
	v_exp_f32_e32 v27, v27
	v_sub_f32_e32 v28, v28, v74
	v_add_f32_e32 v54, v24, v54
	v_exp_f32_e32 v28, v28
	v_sub_f32_e32 v29, v29, v74
	v_add_f32_e32 v54, v25, v54
	v_exp_f32_e32 v29, v29
	v_sub_f32_e32 v58, v178, v74
	s_and_b32 s12, s86, 2
	s_or_b32 s12, s12, s87
	v_lshl_add_u32 v231, s12, 14, v201
	ds_read_b64_tr_b16 v[164:165], v231 offset:0
	ds_read_b64_tr_b16 v[166:167], v231 offset:0x800
	ds_read_b64_tr_b16 v[168:169], v231 offset:0x200
	ds_read_b64_tr_b16 v[170:171], v231 offset:0xa00
	ds_read_b64_tr_b16 v[172:173], v231 offset:0x1000
	ds_read_b64_tr_b16 v[174:175], v231 offset:0x1800
	ds_read_b64_tr_b16 v[176:177], v231 offset:0x1200
	ds_read_b64_tr_b16 v[178:179], v231 offset:0x1a00
	v_add_f32_e32 v54, v26, v54
	v_exp_f32_e32 v61, v58
	v_sub_f32_e32 v31, v31, v74
	v_add_f32_e32 v54, v27, v54
	v_exp_f32_e32 v31, v31
	v_add_f32_e32 v54, v28, v54
	v_add_f32_e32 v54, v29, v54
	v_add_f32_e32 v54, v61, v54
	v_add_f32_e32 v62, v31, v54
	v_cvt_pk_bf16_f32 v54, v16, v17
	v_cvt_pk_bf16_f32 v55, v32, v55
	v_cvt_pk_bf16_f32 v56, v56, v57
	v_cvt_pk_bf16_f32 v57, v22, v23
	v_cvt_pk_bf16_f32 v58, v24, v25
	v_cvt_pk_bf16_f32 v59, v26, v27
	v_cvt_pk_bf16_f32 v60, v28, v29
	v_cvt_pk_bf16_f32 v61, v61, v31
	v_permlane32_swap_b32_e32 v54, v56
	v_permlane32_swap_b32_e32 v55, v57
	v_permlane32_swap_b32_e32 v58, v60
	v_permlane32_swap_b32_e32 v59, v61
	v_sub_f32_e32 v16, v30, v74
	v_exp_f32_e32 v16, v16
	v_sub_f32_e32 v17, v33, v74
	v_exp_f32_e32 v17, v17
	v_sub_f32_e32 v2, v2, v74
	v_exp_f32_e32 v2, v2
	v_sub_f32_e32 v3, v3, v74
	v_exp_f32_e32 v3, v3
	v_sub_f32_e32 v4, v4, v74
	v_add_f32_e32 v22, v16, v62
	v_exp_f32_e32 v4, v4
	v_sub_f32_e32 v5, v5, v74
	v_add_f32_e32 v22, v17, v22
	v_exp_f32_e32 v5, v5
	v_sub_f32_e32 v6, v6, v74
	v_add_f32_e32 v22, v2, v22
	v_exp_f32_e32 v6, v6
	v_sub_f32_e32 v7, v7, v74
	v_add_f32_e32 v22, v3, v22
	v_exp_f32_e32 v7, v7
	v_sub_f32_e32 v8, v8, v74
	v_add_f32_e32 v22, v4, v22
	v_exp_f32_e32 v8, v8
	v_sub_f32_e32 v9, v9, v74
	v_add_f32_e32 v22, v5, v22
	v_exp_f32_e32 v9, v9
	v_sub_f32_e32 v10, v10, v74
	v_add_f32_e32 v22, v6, v22
	v_exp_f32_e32 v10, v10
	v_sub_f32_e32 v11, v11, v74
	v_add_f32_e32 v22, v7, v22
	v_exp_f32_e32 v11, v11
	v_sub_f32_e32 v12, v12, v74
	v_add_f32_e32 v22, v8, v22
	v_exp_f32_e32 v12, v12
	v_sub_f32_e32 v13, v13, v74
	v_add_f32_e32 v22, v9, v22
	v_exp_f32_e32 v13, v13
	v_sub_f32_e32 v14, v14, v74
	v_add_f32_e32 v22, v10, v22
	v_exp_f32_e32 v14, v14
	v_sub_f32_e32 v15, v15, v74
	v_add_f32_e32 v22, v11, v22
	v_exp_f32_e32 v15, v15
	v_add_f32_e32 v22, v12, v22
	v_add_f32_e32 v22, v13, v22
	v_add_f32_e32 v22, v14, v22
	v_add_f32_e32 v22, v15, v22
	v_cvt_pk_bf16_f32 v62, v16, v17
	v_cvt_pk_bf16_f32 v63, v2, v3
	v_cvt_pk_bf16_f32 v64, v4, v5
	v_cvt_pk_bf16_f32 v65, v6, v7
	v_cvt_pk_bf16_f32 v66, v8, v9
	v_cvt_pk_bf16_f32 v67, v10, v11
	v_cvt_pk_bf16_f32 v68, v12, v13
	v_cvt_pk_bf16_f32 v69, v14, v15
	v_permlane32_swap_b32_e32 v62, v64
	v_permlane32_swap_b32_e32 v63, v65
	v_permlane32_swap_b32_e32 v66, v68
	v_permlane32_swap_b32_e32 v67, v69
	v_mov_b32_e32 v2, v22
	s_and_b32 s12, s86, 2
	s_nop 0
	v_permlane32_swap_b32_e32 v22, v2
	s_or_b32 s12, s12, s87
	v_add_f32_e32 v70, v22, v2
	v_lshl_add_u32 v6, s12, 14, v201
	s_waitcnt lgkmcnt(0)
; __device__ __forceinline__ int crow(int r, int hi) { return (r & 3) + 8 * (r >> 2) + 4 * hi; }
; __device__ __forceinline__ unsigned cvtpk(float lo, float hi) { f32x2_t v = {lo, hi}; bf16x2_t b = __builtin_convertvector(v, bf16x2_t); return __builtin_bit_cast(unsigned, b); }
; __device__ __forceinline__ void mixa_run(int b, int h, int br, int res, int n0, const bf16_t* __restrict__ proj, const float* __restrict__ btab,
;                                          bf16_t* __restrict__ OA, float* __restrict__ LSE, char* lds) {
;     ...
;     MIXA_PV(0); MIXA_PV(1); MIXA_PV(2); MIXA_PV(3); MIXA_PV(4);
;     ...
;     if (hi == 0) li_l[r32] = sum; asm volatile("s_waitcnt lgkmcnt(0)" ::: "memory");
;     {
;       char* ub = (char*)Ob0 + ((rowb + ((size_t)(64 * nq + 32 * q32) << sh) + res) * 1024) * 2;
;       const unsigned loff = (((unsigned)(4 * hi) << sh) * 1024u + (unsigned)r32) * 2u;
; #pragma unroll
;       for (int r = 0; r < 16; ++r) { const float rl = __builtin_amdgcn_rcpf(li_l[crow(r, hi)]);
;         const unsigned w = cvtpk(o0[r] * rl, o1[r] * rl);
;         bf16_t* dst = (bf16_t*)(ub + ((size_t)(((r & 3) + 8 * (r >> 2)) << sh) * 2048) + loff);
;         dst[0] = (bf16_t)(w & 0xffffu); dst[32] = (bf16_t)(w >> 16); } }
	s_nop 0
	v_mfma_f32_32x32x16_bf16 v[2:17], v[18:21], v[164:167], 0
	v_add_u32_e32 v71, s69, v213
	v_mfma_f32_32x32x16_bf16 v[18:33], v[18:21], v[168:171], 0
	v_mfma_f32_32x32x16_bf16 v[2:17], v[34:37], v[172:175], v[2:17]
	v_mfma_f32_32x32x16_bf16 v[18:33], v[34:37], v[176:179], v[18:33]
	ds_read_b64_tr_b16 v[34:35], v71 offset:0
	ds_read_b64_tr_b16 v[36:37], v71 offset:0x800
	ds_read_b64_tr_b16 v[76:77], v71 offset:0x200
	ds_read_b64_tr_b16 v[78:79], v71 offset:0xa00
	ds_read_b64_tr_b16 v[160:161], v71 offset:0x1000
	ds_read_b64_tr_b16 v[162:163], v71 offset:0x1800
	ds_read_b64_tr_b16 v[164:165], v71 offset:0x1200
	ds_read_b64_tr_b16 v[166:167], v71 offset:0x1a00
	s_waitcnt lgkmcnt(0)
	s_nop 0
	v_mfma_f32_32x32x16_bf16 v[2:17], v[38:41], v[34:37], v[2:17]
	v_add_u32_e32 v71, s25, v201
	ds_read_b64_tr_b16 v[34:35], v71 offset:0
	ds_read_b64_tr_b16 v[36:37], v71 offset:0x800
	v_mfma_f32_32x32x16_bf16 v[18:33], v[38:41], v[76:79], v[18:33]
	ds_read_b64_tr_b16 v[38:39], v71 offset:0x200
	ds_read_b64_tr_b16 v[40:41], v71 offset:0xa00
	v_mfma_f32_32x32x16_bf16 v[2:17], v[42:45], v[160:163], v[2:17]
	v_mfma_f32_32x32x16_bf16 v[18:33], v[42:45], v[164:167], v[18:33]
	ds_read_b64_tr_b16 v[42:43], v71 offset:0x1000
	ds_read_b64_tr_b16 v[44:45], v71 offset:0x1800
	ds_read_b64_tr_b16 v[76:77], v71 offset:0x1200
	ds_read_b64_tr_b16 v[78:79], v71 offset:0x1a00
	s_waitcnt lgkmcnt(0)
	v_mfma_f32_32x32x16_bf16 v[2:17], v[46:49], v[34:37], v[2:17]
	v_mfma_f32_32x32x16_bf16 v[18:33], v[46:49], v[38:41], v[18:33]
	v_mfma_f32_32x32x16_bf16 v[2:17], v[50:53], v[42:45], v[2:17]
	v_mfma_f32_32x32x16_bf16 v[18:33], v[50:53], v[76:79], v[18:33]
	v_add_u32_e32 v50, s26, v214
	ds_read_b64_tr_b16 v[34:35], v50 offset:0
	ds_read_b64_tr_b16 v[36:37], v50 offset:0x800
	ds_read_b64_tr_b16 v[38:39], v50 offset:0x200
	ds_read_b64_tr_b16 v[40:41], v50 offset:0xa00
	ds_read_b64_tr_b16 v[42:43], v50 offset:0x1000
	ds_read_b64_tr_b16 v[44:45], v50 offset:0x1800
	ds_read_b64_tr_b16 v[46:47], v50 offset:0x1200
	ds_read_b64_tr_b16 v[48:49], v50 offset:0x1a00
	s_waitcnt lgkmcnt(0)
	s_nop 0
	v_mfma_f32_32x32x16_bf16 v[2:17], v[54:57], v[34:37], v[2:17]
	s_add_i32 s68, s68, 0x8000
	s_and_b32 s12, s68, 0xc000
	v_add_u32_e32 v50, s12, v201
	ds_read_b64_tr_b16 v[34:35], v50 offset:0
	ds_read_b64_tr_b16 v[36:37], v50 offset:0x800
	v_mfma_f32_32x32x16_bf16 v[18:33], v[54:57], v[38:41], v[18:33]
	ds_read_b64_tr_b16 v[38:39], v50 offset:0x200
	ds_read_b64_tr_b16 v[40:41], v50 offset:0xa00
	v_mfma_f32_32x32x16_bf16 v[2:17], v[58:61], v[42:45], v[2:17]
	ds_read_b64_tr_b16 v[42:43], v50 offset:0x1000
	ds_read_b64_tr_b16 v[44:45], v50 offset:0x1800
	v_mfma_f32_32x32x16_bf16 v[18:33], v[58:61], v[46:49], v[18:33]
	ds_read_b64_tr_b16 v[46:47], v50 offset:0x1200
	ds_read_b64_tr_b16 v[48:49], v50 offset:0x1a00
	s_waitcnt lgkmcnt(0)
	v_mfma_f32_32x32x16_bf16 v[2:17], v[62:65], v[34:37], v[2:17]
	v_mfma_f32_32x32x16_bf16 v[18:33], v[62:65], v[38:41], v[18:33]
	v_mfma_f32_32x32x16_bf16 v[2:17], v[66:69], v[42:45], v[2:17]
	v_mfma_f32_32x32x16_bf16 v[18:33], v[66:69], v[46:49], v[18:33]
	s_and_saveexec_b64 s[12:13], s[40:41]
	ds_write_b32 v215, v70
	s_or_b64 exec, exec, s[12:13]
	s_waitcnt lgkmcnt(0)
	ds_read_b128 v[34:37], v229
	ds_read_b128 v[38:41], v229 offset:32
	s_add_u32 s12, s24, s10
	s_addc_u32 s13, 0, s11
	s_lshl_b64 s[12:13], s[12:13], s29
	s_waitcnt lgkmcnt(1)
	v_rcp_f32_e32 v34, v34
	s_add_u32 s12, s12, s46
	s_addc_u32 s13, s13, s47
	v_mov_b32_e32 v44, v2
	v_mov_b32_e32 v45, v18
	v_rcp_f32_e32 v2, v35
	s_lshl_b64 s[12:13], s[12:13], 11
	v_pk_mul_f32 v[44:45], v[44:45], v[34:35] op_sel_hi:[1,0]
	v_lshl_add_u64 v[42:43], v[156:157], 0, s[12:13]
	v_cvt_pk_bf16_f32 v18, v44, v45
	global_store_short v[42:43], v18, off
	global_store_short_d16_hi v[42:43], v18, off offset:64
	v_mov_b32_e32 v18, v3
	v_pk_mul_f32 v[2:3], v[18:19], v[2:3] op_sel_hi:[1,0]
	v_rcp_f32_e32 v18, v36
	v_cvt_pk_bf16_f32 v19, v2, v3
	v_lshl_add_u64 v[2:3], v[42:43], 0, s[62:63]
	global_store_short v[2:3], v19, off
	global_store_short_d16_hi v[2:3], v19, off offset:64
	v_mov_b32_e32 v2, v4
	v_rcp_f32_e32 v4, v37
	v_mov_b32_e32 v3, v20
	v_pk_mul_f32 v[2:3], v[2:3], v[18:19] op_sel_hi:[1,0]
	v_mov_b32_e32 v20, v5
	v_cvt_pk_bf16_f32 v18, v2, v3
	v_lshl_add_u64 v[2:3], v[42:43], 0, s[74:75]
	global_store_short v[2:3], v18, off
	global_store_short_d16_hi v[2:3], v18, off offset:64
	v_pk_mul_f32 v[2:3], v[20:21], v[4:5] op_sel_hi:[1,0]
	s_waitcnt lgkmcnt(0)
; __device__ __forceinline__ int crow(int r, int hi) { return (r & 3) + 8 * (r >> 2) + 4 * hi; }
; __device__ __forceinline__ unsigned cvtpk(float lo, float hi) { f32x2_t v = {lo, hi}; bf16x2_t b = __builtin_convertvector(v, bf16x2_t); return __builtin_bit_cast(unsigned, b); }
; __device__ __forceinline__ void mixa_run(int b, int h, int br, int res, int n0, const bf16_t* __restrict__ proj, const float* __restrict__ btab,
;                                          bf16_t* __restrict__ OA, float* __restrict__ LSE, char* lds) {
;     ...
;     if (hi == 0) li_l[r32] = sum; asm volatile("s_waitcnt lgkmcnt(0)" ::: "memory");
;     {
;       char* ub = (char*)Ob0 + ((rowb + ((size_t)(64 * nq + 32 * q32) << sh) + res) * 1024) * 2;
;       const unsigned loff = (((unsigned)(4 * hi) << sh) * 1024u + (unsigned)r32) * 2u;
; #pragma unroll
;       for (int r = 0; r < 16; ++r) { const float rl = __builtin_amdgcn_rcpf(li_l[crow(r, hi)]);
;         const unsigned w = cvtpk(o0[r] * rl, o1[r] * rl);
;         bf16_t* dst = (bf16_t*)(ub + ((size_t)(((r & 3) + 8 * (r >> 2)) << sh) * 2048) + loff);
;         dst[0] = (bf16_t)(w & 0xffffu); dst[32] = (bf16_t)(w >> 16); } }
;     if (dh == 0 && hi == 0) Lb[tokq * 8] = (mx + __builtin_amdgcn_logf(sum)) * 0.6931471805599453f;
	v_rcp_f32_e32 v4, v38
	v_cvt_pk_bf16_f32 v5, v2, v3
	v_lshl_add_u64 v[2:3], v[42:43], 0, s[82:83]
	global_store_short v[2:3], v5, off
	global_store_short_d16_hi v[2:3], v5, off offset:64
	v_mov_b32_e32 v2, v6
	v_mov_b32_e32 v3, v22
	v_pk_mul_f32 v[2:3], v[2:3], v[4:5] op_sel_hi:[1,0]
	v_rcp_f32_e32 v4, v39
	v_cvt_pk_bf16_f32 v5, v2, v3
	v_lshl_add_u64 v[2:3], v[42:43], 0, s[34:35]
	v_mov_b32_e32 v22, v7
	global_store_short v[2:3], v5, off
	global_store_short_d16_hi v[2:3], v5, off offset:64
	v_pk_mul_f32 v[2:3], v[22:23], v[4:5] op_sel_hi:[1,0]
	v_rcp_f32_e32 v4, v40
	v_cvt_pk_bf16_f32 v5, v2, v3
	v_lshl_add_u64 v[2:3], v[42:43], 0, s[90:91]
	global_store_short v[2:3], v5, off
	global_store_short_d16_hi v[2:3], v5, off offset:64
	v_mov_b32_e32 v2, v8
	v_mov_b32_e32 v3, v24
	v_pk_mul_f32 v[2:3], v[2:3], v[4:5] op_sel_hi:[1,0]
	v_rcp_f32_e32 v4, v41
	v_cvt_pk_bf16_f32 v5, v2, v3
	v_lshl_add_u64 v[2:3], v[42:43], 0, s[66:67]
	global_store_short v[2:3], v5, off
	global_store_short_d16_hi v[2:3], v5, off offset:64
	v_mov_b32_e32 v24, v9
	v_pk_mul_f32 v[6:7], v[24:25], v[4:5] op_sel_hi:[1,0]
	ds_read_b128 v[2:5], v229 offset:64
	v_cvt_pk_bf16_f32 v20, v6, v7
	ds_read_b128 v[6:9], v229 offset:96
	v_lshl_add_u64 v[18:19], v[42:43], 0, s[88:89]
	global_store_short v[18:19], v20, off
	s_waitcnt lgkmcnt(1)
	v_rcp_f32_e32 v2, v2
	global_store_short_d16_hi v[18:19], v20, off offset:64
	v_mov_b32_e32 v18, v10
	v_mov_b32_e32 v19, v26
	v_pk_mul_f32 v[18:19], v[18:19], v[2:3] op_sel_hi:[1,0]
	v_rcp_f32_e32 v2, v3
	v_mov_b32_e32 v26, v11
	v_rcp_f32_e32 v4, v4
	v_cvt_pk_bf16_f32 v10, v18, v19
	v_lshl_add_u64 v[18:19], v[42:43], 0, s[36:37]
	v_pk_mul_f32 v[2:3], v[26:27], v[2:3] op_sel_hi:[1,0]
	global_store_short v[18:19], v10, off
	global_store_short_d16_hi v[18:19], v10, off offset:64
	v_cvt_pk_bf16_f32 v10, v2, v3
	v_lshl_add_u64 v[2:3], v[42:43], 0, s[92:93]
	global_store_short v[2:3], v10, off
	global_store_short_d16_hi v[2:3], v10, off offset:64
	v_mov_b32_e32 v2, v12
	v_mov_b32_e32 v3, v28
	v_pk_mul_f32 v[2:3], v[2:3], v[4:5] op_sel_hi:[1,0]
	v_rcp_f32_e32 v4, v5
	v_cvt_pk_bf16_f32 v10, v2, v3
	v_lshl_add_u64 v[2:3], v[42:43], 0, s[94:95]
	v_mov_b32_e32 v28, v13
	global_store_short v[2:3], v10, off
	global_store_short_d16_hi v[2:3], v10, off offset:64
	v_pk_mul_f32 v[2:3], v[28:29], v[4:5] op_sel_hi:[1,0]
	s_waitcnt lgkmcnt(0)
	v_rcp_f32_e32 v4, v6
	v_cvt_pk_bf16_f32 v5, v2, v3
	v_lshl_add_u64 v[2:3], v[42:43], 0, s[96:97]
	global_store_short v[2:3], v5, off
	global_store_short_d16_hi v[2:3], v5, off offset:64
	v_mov_b32_e32 v2, v14
	v_mov_b32_e32 v3, v30
	v_pk_mul_f32 v[2:3], v[2:3], v[4:5] op_sel_hi:[1,0]
	v_rcp_f32_e32 v4, v7
	v_cvt_pk_bf16_f32 v5, v2, v3
	v_lshl_add_u64 v[2:3], v[42:43], 0, s[78:79]
	v_mov_b32_e32 v30, v15
	global_store_short v[2:3], v5, off
	global_store_short_d16_hi v[2:3], v5, off offset:64
	v_pk_mul_f32 v[2:3], v[30:31], v[4:5] op_sel_hi:[1,0]
	v_rcp_f32_e32 v4, v8
	v_cvt_pk_bf16_f32 v5, v2, v3
	v_lshl_add_u64 v[2:3], v[42:43], 0, s[76:77]
	global_store_short v[2:3], v5, off
	global_store_short_d16_hi v[2:3], v5, off offset:64
	v_mov_b32_e32 v2, v16
	v_mov_b32_e32 v3, v32
	v_pk_mul_f32 v[2:3], v[2:3], v[4:5] op_sel_hi:[1,0]
	v_rcp_f32_e32 v4, v9
	v_cvt_pk_bf16_f32 v5, v2, v3
	v_lshl_add_u64 v[2:3], v[42:43], 0, s[6:7]
	v_mov_b32_e32 v32, v17
	global_store_short v[2:3], v5, off
	global_store_short_d16_hi v[2:3], v5, off offset:64
	v_pk_mul_f32 v[2:3], v[32:33], v[4:5] op_sel_hi:[1,0]
	s_nop 0
	v_cvt_pk_bf16_f32 v4, v2, v3
	v_lshl_add_u64 v[2:3], v[42:43], 0, s[8:9]
	global_store_short v[2:3], v4, off
	global_store_short_d16_hi v[2:3], v4, off offset:64
	s_and_saveexec_b64 s[12:13], s[52:53]
	s_mov_b64 s[68:69], s[18:19]
	s_cbranch_execz .LBB0_323
	v_log_f32_e32 v4, v70
	v_lshlrev_b64 v[2:3], s29, v[116:117]
	v_lshl_add_u64 v[2:3], v[2:3], 0, s[46:47]
	v_lshlrev_b64 v[2:3], 5, v[2:3]
	v_add_f32_e32 v4, v74, v4
	v_mul_f32_e32 v4, 0x3f317218, v4
	v_lshl_add_u64 v[2:3], s[50:51], 0, v[2:3]
	global_store_dword v[2:3], v4, off
